# speedup vs baseline: 1.0065x; 1.0065x over previous
; __device__ __forceinline__ void unpack8(u32x4 v, float* f) { f[0] = bflo(v[0]); f[1] = bfhi(v[0]); f[2] = bflo(v[1]); f[3] = bfhi(v[1]); f[4] = bflo(v[2]); f[5] = bfhi(v[2]); f[6] = bflo(v[3]); f[7] = bfhi(v[3]); }
; __device__ __forceinline__ void dn_prep_unit(int layer, int sample, int b, int n, int h, unsigned char* shm) {
;     ...
;             if (tt < rows) {
; #pragma unroll
;                 for (int j = 0; j < 4; ++j) { const int lt = n * 64 + tt - 3 + j; float x[16];
;                     if (lt >= 0) { const bf16_t* s = P + (tokb + lt) * NINP + C_DQ + ch; unpack8(*(const u32x4*)s, x); unpack8(*(const u32x4*)(s + 8), x + 8); }
;                     else if (sample) { const float* s = p->in[8] + (((size_t)layer * 16 + b) * 3 + (3 + lt)) * 3072 + ch;
; #pragma unroll
;                         for (int i = 0; i < 16; ++i) x[i] = s[i]; }
;                     else {
; #pragma unroll
;                         for (int i = 0; i < 16; ++i) x[i] = 0.f; }
.Lfc0_entry:
	v_or_b32_e32 v128, v134, v114
	v_cmp_gt_i32_e32 vcc, 3, v124
	s_and_saveexec_b64 s[22:23], vcc
	s_xor_b64 s[22:23], exec, s[22:23]
	s_cbranch_execz .Lfc0_961
	v_mov_b32_e32 v5, 0
	v_mov_b32_e32 v4, 0
	v_mov_b32_e32 v3, 0
	v_mov_b32_e32 v2, 0
	v_mov_b32_e32 v13, 0
	v_mov_b32_e32 v12, 0
	v_mov_b32_e32 v11, 0
	v_mov_b32_e32 v10, 0
	v_mov_b32_e32 v9, 0
	v_mov_b32_e32 v8, 0
	v_mov_b32_e32 v7, 0
	v_mov_b32_e32 v6, 0
	v_mov_b32_e32 v17, 0
	v_mov_b32_e32 v16, 0
	v_mov_b32_e32 v15, 0
	v_mov_b32_e32 v14, 0
	s_and_saveexec_b64 s[24:25], s[6:7]
	s_cbranch_execz .Lfc0_960
	s_load_dwordx2 s[38:39], s[18:19], 0x40
	v_ashrrev_i32_e32 v125, 31, v124
	v_lshl_add_u64 v[2:3], v[120:121], 0, v[124:125]
	s_waitcnt lgkmcnt(0)
	v_mov_b64_e32 v[4:5], s[38:39]
	v_mad_u64_u32 v[4:5], s[38:39], v2, s69, v[4:5]
	v_mov_b32_e32 v2, v5
	v_mad_u64_u32 v[2:3], s[38:39], v3, s69, v[2:3]
	v_mov_b32_e32 v5, v2
	v_lshlrev_b32_e32 v2, 2, v128
	v_mov_b32_e32 v3, v0
	v_lshl_add_u64 v[2:3], v[4:5], 0, v[2:3]
	global_load_dwordx4 v[14:17], v[2:3], off
	global_load_dwordx4 v[6:9], v[2:3], off offset:16
	global_load_dwordx4 v[10:13], v[2:3], off offset:32
	s_nop 0
	global_load_dwordx4 v[2:5], v[2:3], off offset:48

; __device__ __forceinline__ void unpack8(u32x4 v, float* f) { f[0] = bflo(v[0]); f[1] = bfhi(v[0]); f[2] = bflo(v[1]); f[3] = bfhi(v[1]); f[4] = bflo(v[2]); f[5] = bfhi(v[2]); f[6] = bflo(v[3]); f[7] = bfhi(v[3]); }
; __device__ __forceinline__ void dn_prep_unit(int layer, int sample, int b, int n, int h, unsigned char* shm) {
;     ...
;             if (tt < rows) {
; #pragma unroll
;                 for (int j = 0; j < 4; ++j) { const int lt = n * 64 + tt - 3 + j; float x[16];
;                     if (lt >= 0) { const bf16_t* s = P + (tokb + lt) * NINP + C_DQ + ch; unpack8(*(const u32x4*)s, x); unpack8(*(const u32x4*)(s + 8), x + 8); }
.Lfc0_961:
	s_andn2_saveexec_b64 s[22:23], s[22:23]
	s_cbranch_execz .Lfc0_963
	v_mov_b32_e32 v127, v0
	s_waitcnt vmcnt(0)
	v_lshl_add_u64 v[2:3], v[118:119], 0, v[126:127]
	v_mov_b64_e32 v[4:5], s[16:17]
	v_mad_u64_u32 v[4:5], s[24:25], v2, s68, v[4:5]
	v_mov_b32_e32 v2, v5
	v_mad_u64_u32 v[2:3], s[24:25], v3, s68, v[2:3]
	v_mov_b32_e32 v5, v2
	v_lshlrev_b32_e32 v2, 1, v128
	v_mov_b32_e32 v3, v0
	v_lshl_add_u64 v[6:7], v[4:5], 0, v[2:3]
	v_add_co_u32_e32 v2, vcc, s97, v6
	s_mov_b64 s[24:25], 0x1000
	s_nop 0
	v_addc_co_u32_e32 v3, vcc, 0, v7, vcc
	v_lshl_add_u64 v[6:7], v[6:7], 0, s[24:25]
	global_load_dwordx4 v[2:5], v[2:3], off
	s_nop 0
	global_load_dwordx4 v[18:21], v[6:7], off offset:16
	v_add_u32_e32 v34, -2, v124
	v_mov_b32_e32 v35, v0
	v_lshl_add_u64 v[34:35], v[118:119], 0, v[34:35]
	v_mov_b64_e32 v[36:37], s[16:17]
	v_mad_u64_u32 v[36:37], s[24:25], v34, s68, v[36:37]
	v_mov_b32_e32 v34, v37
	v_mad_u64_u32 v[34:35], s[24:25], v35, s68, v[34:35]
	v_mov_b32_e32 v37, v34
	v_lshlrev_b32_e32 v34, 1, v128
	v_mov_b32_e32 v35, v0
	v_lshl_add_u64 v[38:39], v[36:37], 0, v[34:35]
	v_add_co_u32_e32 v34, vcc, s97, v38
	s_mov_b64 s[24:25], 0x1000
	s_nop 0
	v_addc_co_u32_e32 v35, vcc, 0, v39, vcc
	v_lshl_add_u64 v[38:39], v[38:39], 0, s[24:25]
	global_load_dwordx4 v[34:37], v[34:35], off
	s_nop 0
	global_load_dwordx4 v[50:53], v[38:39], off offset:16
	v_add_u32_e32 v66, -1, v124
	v_mov_b32_e32 v67, v0
	v_lshl_add_u64 v[66:67], v[118:119], 0, v[66:67]
	v_mov_b64_e32 v[68:69], s[16:17]
	v_mad_u64_u32 v[68:69], s[24:25], v66, s68, v[68:69]
	v_mov_b32_e32 v66, v69
	v_mad_u64_u32 v[66:67], s[24:25], v67, s68, v[66:67]
	v_mov_b32_e32 v69, v66
	v_lshlrev_b32_e32 v66, 1, v128
	v_mov_b32_e32 v67, v0
	v_lshl_add_u64 v[70:71], v[68:69], 0, v[66:67]
	v_add_co_u32_e32 v66, vcc, s97, v70
	s_mov_b64 s[24:25], 0x1000
	s_nop 0
	v_addc_co_u32_e32 v67, vcc, 0, v71, vcc
	v_lshl_add_u64 v[70:71], v[70:71], 0, s[24:25]
	global_load_dwordx4 v[66:69], v[66:67], off
	s_nop 0
	global_load_dwordx4 v[82:85], v[70:71], off offset:16
	v_mov_b32_e32 v125, v0
	v_lshl_add_u64 v[184:185], v[118:119], 0, v[124:125]
	v_mov_b64_e32 v[186:187], s[16:17]
	v_mad_u64_u32 v[186:187], s[24:25], v184, s68, v[186:187]
	v_mov_b32_e32 v184, v187
	v_mad_u64_u32 v[184:185], s[24:25], v185, s68, v[184:185]
	v_mov_b32_e32 v187, v184
	v_lshlrev_b32_e32 v184, 1, v128
	v_mov_b32_e32 v185, v0
	v_lshl_add_u64 v[188:189], v[186:187], 0, v[184:185]
	v_add_co_u32_e32 v184, vcc, s97, v188
	s_mov_b64 s[24:25], 0x1000
	s_nop 0
	v_addc_co_u32_e32 v185, vcc, 0, v189, vcc
	v_lshl_add_u64 v[188:189], v[188:189], 0, s[24:25]
	global_load_dwordx4 v[184:187], v[184:185], off
	s_nop 0
	global_load_dwordx4 v[190:193], v[188:189], off offset:16
	s_waitcnt vmcnt(1)
	v_lshlrev_b32_e32 v14, 16, v2
	v_and_b32_e32 v15, 0xffff0000, v2
	v_lshlrev_b32_e32 v16, 16, v3
	v_and_b32_e32 v17, 0xffff0000, v3
	v_lshlrev_b32_e32 v6, 16, v4
	v_and_b32_e32 v7, 0xffff0000, v4
	v_lshlrev_b32_e32 v8, 16, v5
	v_and_b32_e32 v9, 0xffff0000, v5
	s_waitcnt vmcnt(0)
	v_lshlrev_b32_e32 v10, 16, v18
	v_and_b32_e32 v11, 0xffff0000, v18
	v_lshlrev_b32_e32 v12, 16, v19
	v_and_b32_e32 v13, 0xffff0000, v19
	v_lshlrev_b32_e32 v2, 16, v20
	v_and_b32_e32 v3, 0xffff0000, v20
	v_lshlrev_b32_e32 v4, 16, v21
	v_and_b32_e32 v5, 0xffff0000, v21

; __device__ __forceinline__ void unpack8(u32x4 v, float* f) { f[0] = bflo(v[0]); f[1] = bfhi(v[0]); f[2] = bflo(v[1]); f[3] = bfhi(v[1]); f[4] = bflo(v[2]); f[5] = bfhi(v[2]); f[6] = bflo(v[3]); f[7] = bfhi(v[3]); }
; __device__ __forceinline__ void dn_prep_unit(int layer, int sample, int b, int n, int h, unsigned char* shm) {
;     ...
;                 for (int j = 0; j < 4; ++j) { const int lt = n * 64 + tt - 3 + j; float x[16];
;                     if (lt >= 0) { const bf16_t* s = P + (tokb + lt) * NINP + C_DQ + ch; unpack8(*(const u32x4*)s, x); unpack8(*(const u32x4*)(s + 8), x + 8); }
.Lfc0_967:
	s_andn2_saveexec_b64 s[22:23], s[22:23]
	s_cbranch_execz .Lfc0_969
	s_waitcnt vmcnt(0)
	s_waitcnt vmcnt(1)
	v_lshlrev_b32_e32 v46, 16, v34
	v_and_b32_e32 v47, 0xffff0000, v34
	v_lshlrev_b32_e32 v48, 16, v35
	v_and_b32_e32 v49, 0xffff0000, v35
	v_lshlrev_b32_e32 v38, 16, v36
	v_and_b32_e32 v39, 0xffff0000, v36
	v_lshlrev_b32_e32 v40, 16, v37
	v_and_b32_e32 v41, 0xffff0000, v37
	s_waitcnt vmcnt(0)
	v_lshlrev_b32_e32 v42, 16, v50
	v_and_b32_e32 v43, 0xffff0000, v50
	v_lshlrev_b32_e32 v44, 16, v51
	v_and_b32_e32 v45, 0xffff0000, v51
	v_lshlrev_b32_e32 v34, 16, v52
	v_and_b32_e32 v35, 0xffff0000, v52
	v_lshlrev_b32_e32 v36, 16, v53
	v_and_b32_e32 v37, 0xffff0000, v53

; __device__ __forceinline__ void unpack8(u32x4 v, float* f) { f[0] = bflo(v[0]); f[1] = bfhi(v[0]); f[2] = bflo(v[1]); f[3] = bfhi(v[1]); f[4] = bflo(v[2]); f[5] = bfhi(v[2]); f[6] = bflo(v[3]); f[7] = bfhi(v[3]); }
; __device__ __forceinline__ void dn_prep_unit(int layer, int sample, int b, int n, int h, unsigned char* shm) {
;     ...
;                 for (int j = 0; j < 4; ++j) { const int lt = n * 64 + tt - 3 + j; float x[16];
;                     if (lt >= 0) { const bf16_t* s = P + (tokb + lt) * NINP + C_DQ + ch; unpack8(*(const u32x4*)s, x); unpack8(*(const u32x4*)(s + 8), x + 8); }
.Lfc0_973:
	s_andn2_saveexec_b64 s[22:23], s[22:23]
	s_cbranch_execz .Lfc0_975
	s_waitcnt vmcnt(0)
	s_waitcnt vmcnt(1)
	v_lshlrev_b32_e32 v78, 16, v66
	v_and_b32_e32 v79, 0xffff0000, v66
	v_lshlrev_b32_e32 v80, 16, v67
	v_and_b32_e32 v81, 0xffff0000, v67
	v_lshlrev_b32_e32 v74, 16, v68
	v_and_b32_e32 v75, 0xffff0000, v68
	v_lshlrev_b32_e32 v76, 16, v69
	v_and_b32_e32 v77, 0xffff0000, v69
	s_waitcnt vmcnt(0)
	v_lshlrev_b32_e32 v70, 16, v82
	v_and_b32_e32 v71, 0xffff0000, v82
	v_lshlrev_b32_e32 v72, 16, v83
	v_and_b32_e32 v73, 0xffff0000, v83
	v_lshlrev_b32_e32 v66, 16, v84
	v_and_b32_e32 v67, 0xffff0000, v84
	v_lshlrev_b32_e32 v68, 16, v85
	v_and_b32_e32 v69, 0xffff0000, v85

; __device__ __forceinline__ void unpack8(u32x4 v, float* f) { f[0] = bflo(v[0]); f[1] = bfhi(v[0]); f[2] = bflo(v[1]); f[3] = bfhi(v[1]); f[4] = bflo(v[2]); f[5] = bfhi(v[2]); f[6] = bflo(v[3]); f[7] = bfhi(v[3]); }
; __device__ __forceinline__ float siluf_(float x) { return x * __builtin_amdgcn_rcpf(1.0f + __expf(-x)); }
; __device__ __forceinline__ void dn_prep_unit(int layer, int sample, int b, int n, int h, unsigned char* shm) {
;     ...
;                 for (int j = 0; j < 4; ++j) { const int lt = n * 64 + tt - 3 + j; float x[16];
;                     if (lt >= 0) { const bf16_t* s = P + (tokb + lt) * NINP + C_DQ + ch; unpack8(*(const u32x4*)s, x); unpack8(*(const u32x4*)(s + 8), x + 8); }
;                     else if (sample) { const float* s = p->in[8] + (((size_t)layer * 16 + b) * 3 + (3 + lt)) * 3072 + ch;
; #pragma unroll
;                         for (int i = 0; i < 16; ++i) x[i] = s[i]; }
;                     else {
; #pragma unroll
;                         for (int i = 0; i < 16; ++i) x[i] = 0.f; }
;                     const float* w = WL + (sel * 4 + j) * 128 + part * 16;
; #pragma unroll
;                     for (int i = 0; i < 16; ++i) y[i] += x[i] * w[i]; }
; #pragma unroll
;                 for (int i = 0; i < 16; ++i) y[i] = siluf_(y[i]);
.Lfc0_979:
	s_andn2_saveexec_b64 s[22:23], s[22:23]
	s_cbranch_execz .Lfc0_981
	v_mov_b32_e32 v125, v0
	s_waitcnt vmcnt(0)
	s_waitcnt vmcnt(1)
	v_lshlrev_b32_e32 v110, 16, v184
	v_and_b32_e32 v111, 0xffff0000, v184
	v_lshlrev_b32_e32 v112, 16, v185
	v_and_b32_e32 v113, 0xffff0000, v185
	v_lshlrev_b32_e32 v102, 16, v186
	v_and_b32_e32 v103, 0xffff0000, v186
	v_lshlrev_b32_e32 v104, 16, v187
	v_and_b32_e32 v105, 0xffff0000, v187
	s_waitcnt vmcnt(0)
	v_lshlrev_b32_e32 v86, 16, v190
	v_and_b32_e32 v87, 0xffff0000, v190
	v_lshlrev_b32_e32 v88, 16, v191
	v_and_b32_e32 v89, 0xffff0000, v191
	v_lshlrev_b32_e32 v82, 16, v192
	v_and_b32_e32 v83, 0xffff0000, v192
	v_lshlrev_b32_e32 v84, 16, v193
	v_and_b32_e32 v85, 0xffff0000, v193
.Lfc0_981:
	s_or_b64 exec, exec, s[22:23]
	s_waitcnt vmcnt(0) lgkmcnt(8)
	v_pk_fma_f32 v[2:3], v[2:3], v[18:19], 0 op_sel_hi:[1,1,0]
	v_pk_fma_f32 v[4:5], v[4:5], v[20:21], 0 op_sel_hi:[1,1,0]
	s_waitcnt lgkmcnt(4)
	v_pk_fma_f32 v[18:19], v[34:35], v[50:51], v[2:3]
	v_pk_fma_f32 v[20:21], v[36:37], v[52:53], v[4:5]
	ds_read_b128 v[2:5], v129 offset:1536
	v_pk_fma_f32 v[16:17], v[16:17], v[32:33], 0 op_sel_hi:[1,1,0]
	v_pk_fma_f32 v[6:7], v[6:7], v[26:27], 0 op_sel_hi:[1,1,0]
	v_pk_fma_f32 v[8:9], v[8:9], v[28:29], 0 op_sel_hi:[1,1,0]
	v_pk_fma_f32 v[16:17], v[48:49], v[64:65], v[16:17]
	v_pk_fma_f32 v[10:11], v[10:11], v[22:23], 0 op_sel_hi:[1,1,0]
	v_pk_fma_f32 v[6:7], v[38:39], v[58:59], v[6:7]
	v_pk_fma_f32 v[8:9], v[40:41], v[60:61], v[8:9]
	s_waitcnt lgkmcnt(4)
	v_pk_fma_f32 v[22:23], v[80:81], v[108:109], v[16:17]
	v_pk_fma_f32 v[12:13], v[12:13], v[24:25], 0 op_sel_hi:[1,1,0]
	s_waitcnt lgkmcnt(3)
	v_pk_fma_f32 v[24:25], v[74:75], v[98:99], v[6:7]
	v_pk_fma_f32 v[26:27], v[76:77], v[100:101], v[8:9]
	ds_read_b128 v[6:9], v129 offset:1552
	s_waitcnt lgkmcnt(1)
	v_pk_fma_f32 v[22:23], v[112:113], v[4:5], v[22:23]
	v_pk_fma_f32 v[14:15], v[14:15], v[30:31], 0 op_sel_hi:[1,1,0]
	v_mul_f32_e32 v4, 0xbfb8aa3b, v22
	v_exp_f32_e32 v4, v4
	v_mul_f32_e32 v5, 0xbfb8aa3b, v23
	v_exp_f32_e32 v5, v5
	s_waitcnt lgkmcnt(0)
	v_pk_fma_f32 v[24:25], v[102:103], v[6:7], v[24:25]
	v_add_f32_e32 v4, 1.0, v4
	v_pk_fma_f32 v[14:15], v[46:47], v[62:63], v[14:15]
	v_rcp_f32_e32 v34, v4
	v_add_f32_e32 v4, 1.0, v5
	v_mul_f32_e32 v5, 0xbfb8aa3b, v24
	v_pk_fma_f32 v[14:15], v[78:79], v[106:107], v[14:15]
	v_exp_f32_e32 v5, v5
	v_mul_f32_e32 v6, 0xbfb8aa3b, v25
	v_pk_fma_f32 v[10:11], v[42:43], v[54:55], v[10:11]
	v_pk_fma_f32 v[2:3], v[110:111], v[2:3], v[14:15]
	v_exp_f32_e32 v6, v6
	v_pk_fma_f32 v[28:29], v[70:71], v[94:95], v[10:11]
	v_mul_f32_e32 v10, 0xbfb8aa3b, v2
	v_pk_fma_f32 v[12:13], v[44:45], v[56:57], v[12:13]
	v_exp_f32_e32 v32, v10
	v_mul_f32_e32 v10, 0xbfb8aa3b, v3
	v_pk_fma_f32 v[26:27], v[104:105], v[8:9], v[26:27]
	v_pk_fma_f32 v[30:31], v[72:73], v[96:97], v[12:13]
	v_exp_f32_e32 v33, v10
	ds_read_b128 v[10:13], v129 offset:1568
	ds_read_b128 v[14:17], v129 offset:1584
	v_rcp_f32_e32 v35, v4
	v_add_f32_e32 v4, 1.0, v5
	v_mul_f32_e32 v5, 0xbfb8aa3b, v26
	v_rcp_f32_e32 v36, v4
	v_add_f32_e32 v4, 1.0, v6
	v_exp_f32_e32 v5, v5
	v_mul_f32_e32 v6, 0xbfb8aa3b, v27
	v_exp_f32_e32 v6, v6
	s_waitcnt lgkmcnt(1)
	v_pk_fma_f32 v[28:29], v[86:87], v[10:11], v[28:29]
	v_rcp_f32_e32 v37, v4
	v_add_f32_e32 v4, 1.0, v5
	v_mul_f32_e32 v5, 0xbfb8aa3b, v28
	v_rcp_f32_e32 v38, v4
	v_add_f32_e32 v4, 1.0, v6
	v_exp_f32_e32 v5, v5
	v_mul_f32_e32 v6, 0xbfb8aa3b, v29
	v_exp_f32_e32 v6, v6
	v_pk_fma_f32 v[30:31], v[88:89], v[12:13], v[30:31]
	v_rcp_f32_e32 v39, v4
	v_add_f32_e32 v4, 1.0, v5
	v_mul_f32_e32 v5, 0xbfb8aa3b, v30
	v_rcp_f32_e32 v40, v4
	v_add_f32_e32 v4, 1.0, v6
	v_exp_f32_e32 v5, v5
	v_mul_f32_e32 v6, 0xbfb8aa3b, v31
	v_exp_f32_e32 v6, v6
	v_pk_fma_f32 v[18:19], v[66:67], v[90:91], v[18:19]
	v_rcp_f32_e32 v41, v4
	s_waitcnt lgkmcnt(0)
	v_pk_fma_f32 v[18:19], v[82:83], v[14:15], v[18:19]
	v_add_f32_e32 v4, 1.0, v5
	v_mul_f32_e32 v5, 0xbfb8aa3b, v18
	v_rcp_f32_e32 v42, v4
	v_add_f32_e32 v4, 1.0, v6
	v_exp_f32_e32 v5, v5
	v_mul_f32_e32 v6, 0xbfb8aa3b, v19
	v_exp_f32_e32 v6, v6
	v_pk_fma_f32 v[20:21], v[68:69], v[92:93], v[20:21]
	v_rcp_f32_e32 v43, v4
	v_pk_fma_f32 v[20:21], v[84:85], v[16:17], v[20:21]
	v_add_f32_e32 v4, 1.0, v5
	v_mul_f32_e32 v5, 0xbfb8aa3b, v20
	v_rcp_f32_e32 v44, v4
	v_add_f32_e32 v4, 1.0, v6
	v_exp_f32_e32 v5, v5
	v_mul_f32_e32 v6, 0xbfb8aa3b, v21
	v_exp_f32_e32 v6, v6
	v_rcp_f32_e32 v45, v4
	v_add_f32_e32 v4, 1.0, v5
	v_add_f32_e32 v32, 1.0, v32
	v_add_f32_e32 v33, 1.0, v33
	v_rcp_f32_e32 v46, v4
	v_add_f32_e32 v4, 1.0, v6
	v_rcp_f32_e32 v32, v32
	v_rcp_f32_e32 v33, v33
	v_rcp_f32_e32 v47, v4
	v_pk_mul_f32 v[6:7], v[22:23], v[34:35]
	v_pk_mul_f32 v[8:9], v[24:25], v[36:37]
	v_pk_mul_f32 v[4:5], v[2:3], v[32:33]
	v_pk_mul_f32 v[10:11], v[26:27], v[38:39]
	v_pk_mul_f32 v[12:13], v[28:29], v[40:41]
	v_pk_mul_f32 v[14:15], v[30:31], v[42:43]
	v_pk_mul_f32 v[16:17], v[18:19], v[44:45]
	v_pk_mul_f32 v[18:19], v[20:21], v[46:47]
	s_branch .LBB0_982
.Lfc1_entry:
	v_or3_b32 v131, v134, v114, s71
	v_cmp_gt_i32_e32 vcc, 3, v124
	s_and_saveexec_b64 s[22:23], vcc
	s_xor_b64 s[22:23], exec, s[22:23]
	s_cbranch_execz .Lfc1_987
	v_mov_b32_e32 v5, 0
	v_mov_b32_e32 v4, 0
	v_mov_b32_e32 v3, 0
	v_mov_b32_e32 v2, 0
	v_mov_b32_e32 v13, 0
	v_mov_b32_e32 v12, 0
	v_mov_b32_e32 v11, 0
	v_mov_b32_e32 v10, 0
	v_mov_b32_e32 v9, 0
	v_mov_b32_e32 v8, 0
	v_mov_b32_e32 v7, 0
	v_mov_b32_e32 v6, 0
	v_mov_b32_e32 v17, 0
	v_mov_b32_e32 v16, 0
	v_mov_b32_e32 v15, 0
	v_mov_b32_e32 v14, 0
	s_and_saveexec_b64 s[24:25], s[6:7]
	s_cbranch_execz .Lfc1_986
	s_load_dwordx2 s[38:39], s[18:19], 0x40
	v_ashrrev_i32_e32 v125, 31, v124
	v_lshl_add_u64 v[2:3], v[120:121], 0, v[124:125]
	s_waitcnt lgkmcnt(0)
	v_mov_b64_e32 v[4:5], s[38:39]
	v_mad_u64_u32 v[4:5], s[38:39], v2, s69, v[4:5]
	v_mov_b32_e32 v2, v5
	v_mad_u64_u32 v[2:3], s[38:39], v3, s69, v[2:3]
	v_mov_b32_e32 v5, v2
	v_lshlrev_b32_e32 v2, 2, v131
	v_mov_b32_e32 v3, v0
	v_lshl_add_u64 v[2:3], v[4:5], 0, v[2:3]
	global_load_dwordx4 v[14:17], v[2:3], off
	global_load_dwordx4 v[6:9], v[2:3], off offset:16
	global_load_dwordx4 v[10:13], v[2:3], off offset:32
	s_nop 0
	global_load_dwordx4 v[2:5], v[2:3], off offset:48

; __device__ __forceinline__ void unpack8(u32x4 v, float* f) { f[0] = bflo(v[0]); f[1] = bfhi(v[0]); f[2] = bflo(v[1]); f[3] = bfhi(v[1]); f[4] = bflo(v[2]); f[5] = bfhi(v[2]); f[6] = bflo(v[3]); f[7] = bfhi(v[3]); }
; __device__ __forceinline__ void dn_prep_unit(int layer, int sample, int b, int n, int h, unsigned char* shm) {
;     ...
;             if (tt < rows) {
; #pragma unroll
;                 for (int j = 0; j < 4; ++j) { const int lt = n * 64 + tt - 3 + j; float x[16];
;                     if (lt >= 0) { const bf16_t* s = P + (tokb + lt) * NINP + C_DQ + ch; unpack8(*(const u32x4*)s, x); unpack8(*(const u32x4*)(s + 8), x + 8); }
.Lfc1_987:
	s_andn2_saveexec_b64 s[22:23], s[22:23]
	s_cbranch_execz .Lfc1_989
	v_mov_b32_e32 v127, v0
	s_waitcnt vmcnt(0)
	v_lshl_add_u64 v[2:3], v[118:119], 0, v[126:127]
	v_mov_b64_e32 v[4:5], s[16:17]
	v_mad_u64_u32 v[4:5], s[24:25], v2, s68, v[4:5]
	v_mov_b32_e32 v2, v5
	v_mad_u64_u32 v[2:3], s[24:25], v3, s68, v[2:3]
	v_mov_b32_e32 v5, v2
	v_lshlrev_b32_e32 v2, 1, v131
	v_mov_b32_e32 v3, v0
	v_lshl_add_u64 v[6:7], v[4:5], 0, v[2:3]
	v_add_co_u32_e32 v2, vcc, s97, v6
	s_mov_b64 s[24:25], 0x1000
	s_nop 0
	v_addc_co_u32_e32 v3, vcc, 0, v7, vcc
	v_lshl_add_u64 v[6:7], v[6:7], 0, s[24:25]
	global_load_dwordx4 v[2:5], v[2:3], off
	s_nop 0
	global_load_dwordx4 v[18:21], v[6:7], off offset:16
	v_add_u32_e32 v34, -2, v124
	v_mov_b32_e32 v35, v0
	v_lshl_add_u64 v[34:35], v[118:119], 0, v[34:35]
	v_mov_b64_e32 v[36:37], s[16:17]
	v_mad_u64_u32 v[36:37], s[24:25], v34, s68, v[36:37]
	v_mov_b32_e32 v34, v37
	v_mad_u64_u32 v[34:35], s[24:25], v35, s68, v[34:35]
	v_mov_b32_e32 v37, v34
	v_lshlrev_b32_e32 v34, 1, v131
	v_mov_b32_e32 v35, v0
	v_lshl_add_u64 v[38:39], v[36:37], 0, v[34:35]
	v_add_co_u32_e32 v34, vcc, s97, v38
	s_mov_b64 s[24:25], 0x1000
	s_nop 0
	v_addc_co_u32_e32 v35, vcc, 0, v39, vcc
	v_lshl_add_u64 v[38:39], v[38:39], 0, s[24:25]
	global_load_dwordx4 v[34:37], v[34:35], off
	s_nop 0
	global_load_dwordx4 v[50:53], v[38:39], off offset:16
	v_add_u32_e32 v66, -1, v124
	v_mov_b32_e32 v67, v0
	v_lshl_add_u64 v[66:67], v[118:119], 0, v[66:67]
	v_mov_b64_e32 v[68:69], s[16:17]
	v_mad_u64_u32 v[68:69], s[24:25], v66, s68, v[68:69]
	v_mov_b32_e32 v66, v69
	v_mad_u64_u32 v[66:67], s[24:25], v67, s68, v[66:67]
	v_mov_b32_e32 v69, v66
	v_lshlrev_b32_e32 v66, 1, v131
	v_mov_b32_e32 v67, v0
	v_lshl_add_u64 v[70:71], v[68:69], 0, v[66:67]
	v_add_co_u32_e32 v66, vcc, s97, v70
	s_mov_b64 s[24:25], 0x1000
	s_nop 0
	v_addc_co_u32_e32 v67, vcc, 0, v71, vcc
	v_lshl_add_u64 v[70:71], v[70:71], 0, s[24:25]
	global_load_dwordx4 v[66:69], v[66:67], off
	s_nop 0
	global_load_dwordx4 v[82:85], v[70:71], off offset:16
	v_mov_b32_e32 v125, v0
	v_lshl_add_u64 v[184:185], v[118:119], 0, v[124:125]
	v_mov_b64_e32 v[186:187], s[16:17]
	v_mad_u64_u32 v[186:187], s[24:25], v184, s68, v[186:187]
	v_mov_b32_e32 v184, v187
	v_mad_u64_u32 v[184:185], s[24:25], v185, s68, v[184:185]
	v_mov_b32_e32 v187, v184
	v_lshlrev_b32_e32 v184, 1, v131
	v_mov_b32_e32 v185, v0
	v_lshl_add_u64 v[188:189], v[186:187], 0, v[184:185]
	v_add_co_u32_e32 v184, vcc, s97, v188
	s_mov_b64 s[24:25], 0x1000
	s_nop 0
	v_addc_co_u32_e32 v185, vcc, 0, v189, vcc
	v_lshl_add_u64 v[188:189], v[188:189], 0, s[24:25]
	global_load_dwordx4 v[184:187], v[184:185], off
	s_nop 0
	global_load_dwordx4 v[190:193], v[188:189], off offset:16
	s_waitcnt vmcnt(1)
	v_lshlrev_b32_e32 v14, 16, v2
	v_and_b32_e32 v15, 0xffff0000, v2
	v_lshlrev_b32_e32 v16, 16, v3
	v_and_b32_e32 v17, 0xffff0000, v3
	v_lshlrev_b32_e32 v6, 16, v4
	v_and_b32_e32 v7, 0xffff0000, v4
	v_lshlrev_b32_e32 v8, 16, v5
	v_and_b32_e32 v9, 0xffff0000, v5
	s_waitcnt vmcnt(0)
	v_lshlrev_b32_e32 v10, 16, v18
	v_and_b32_e32 v11, 0xffff0000, v18
	v_lshlrev_b32_e32 v12, 16, v19
	v_and_b32_e32 v13, 0xffff0000, v19
	v_lshlrev_b32_e32 v2, 16, v20
	v_and_b32_e32 v3, 0xffff0000, v20
	v_lshlrev_b32_e32 v4, 16, v21
	v_and_b32_e32 v5, 0xffff0000, v21

; __device__ __forceinline__ float siluf_(float x) { return x * __builtin_amdgcn_rcpf(1.0f + __expf(-x)); }
; __device__ __forceinline__ void dn_prep_unit(int layer, int sample, int b, int n, int h, unsigned char* shm) {
;     ...
;                     const float* w = WL + (sel * 4 + j) * 128 + part * 16;
; #pragma unroll
;                     for (int i = 0; i < 16; ++i) y[i] += x[i] * w[i]; }
; #pragma unroll
;                 for (int i = 0; i < 16; ++i) y[i] = siluf_(y[i]);
.Lfc1_1007:
	s_or_b64 exec, exec, s[22:23]
	s_waitcnt vmcnt(0) lgkmcnt(8)
	v_pk_fma_f32 v[2:3], v[2:3], v[18:19], 0 op_sel_hi:[1,1,0]
	v_pk_fma_f32 v[4:5], v[4:5], v[20:21], 0 op_sel_hi:[1,1,0]
	s_waitcnt lgkmcnt(4)
	v_pk_fma_f32 v[18:19], v[34:35], v[50:51], v[2:3]
	v_pk_fma_f32 v[20:21], v[36:37], v[52:53], v[4:5]
	ds_read_b128 v[2:5], v129 offset:3584
	v_pk_fma_f32 v[14:15], v[14:15], v[30:31], 0 op_sel_hi:[1,1,0]
	v_pk_fma_f32 v[6:7], v[6:7], v[26:27], 0 op_sel_hi:[1,1,0]
	v_pk_fma_f32 v[8:9], v[8:9], v[28:29], 0 op_sel_hi:[1,1,0]
	v_pk_fma_f32 v[14:15], v[46:47], v[62:63], v[14:15]
	v_pk_fma_f32 v[10:11], v[10:11], v[22:23], 0 op_sel_hi:[1,1,0]
	v_pk_fma_f32 v[6:7], v[38:39], v[58:59], v[6:7]
	v_pk_fma_f32 v[8:9], v[40:41], v[60:61], v[8:9]
	s_waitcnt lgkmcnt(4)
	v_pk_fma_f32 v[14:15], v[78:79], v[106:107], v[14:15]
	v_pk_fma_f32 v[12:13], v[12:13], v[24:25], 0 op_sel_hi:[1,1,0]
	v_pk_fma_f32 v[10:11], v[42:43], v[54:55], v[10:11]
	s_waitcnt lgkmcnt(3)
	v_pk_fma_f32 v[24:25], v[74:75], v[98:99], v[6:7]
	v_pk_fma_f32 v[26:27], v[76:77], v[100:101], v[8:9]
	ds_read_b128 v[6:9], v129 offset:3600
	s_waitcnt lgkmcnt(1)
	v_pk_fma_f32 v[2:3], v[110:111], v[2:3], v[14:15]
	v_pk_fma_f32 v[16:17], v[16:17], v[32:33], 0 op_sel_hi:[1,1,0]
	v_pk_fma_f32 v[28:29], v[70:71], v[94:95], v[10:11]
	v_mul_f32_e32 v10, 0xbfb8aa3b, v2
	v_pk_fma_f32 v[16:17], v[48:49], v[64:65], v[16:17]
	v_pk_fma_f32 v[12:13], v[44:45], v[56:57], v[12:13]
	v_exp_f32_e32 v32, v10
	v_mul_f32_e32 v10, 0xbfb8aa3b, v3
	v_pk_fma_f32 v[22:23], v[80:81], v[108:109], v[16:17]
	v_pk_fma_f32 v[30:31], v[72:73], v[96:97], v[12:13]
	v_exp_f32_e32 v33, v10
	ds_read_b128 v[10:13], v129 offset:3616
	ds_read_b128 v[14:17], v129 offset:3632
	v_pk_fma_f32 v[18:19], v[66:67], v[90:91], v[18:19]
	v_pk_fma_f32 v[20:21], v[68:69], v[92:93], v[20:21]
	v_pk_fma_f32 v[4:5], v[112:113], v[4:5], v[22:23]
	s_waitcnt lgkmcnt(1)
	v_pk_fma_f32 v[30:31], v[88:89], v[12:13], v[30:31]
	s_waitcnt lgkmcnt(0)
	v_pk_fma_f32 v[36:37], v[82:83], v[14:15], v[18:19]
	v_mul_f32_e32 v12, 0xbfb8aa3b, v30
	v_exp_f32_e32 v12, v12
	v_mul_f32_e32 v13, 0xbfb8aa3b, v31
	v_exp_f32_e32 v13, v13
	v_mul_f32_e32 v14, 0xbfb8aa3b, v37
	v_add_f32_e32 v12, 1.0, v12
	v_rcp_f32_e32 v34, v12
	v_add_f32_e32 v12, 1.0, v13
	v_mul_f32_e32 v13, 0xbfb8aa3b, v36
	v_exp_f32_e32 v13, v13
	v_exp_f32_e32 v14, v14
	v_pk_fma_f32 v[20:21], v[84:85], v[16:17], v[20:21]
	v_pk_fma_f32 v[6:7], v[102:103], v[6:7], v[24:25]
	v_pk_fma_f32 v[8:9], v[104:105], v[8:9], v[26:27]
	v_pk_fma_f32 v[10:11], v[86:87], v[10:11], v[28:29]
	v_rcp_f32_e32 v35, v12
	v_add_f32_e32 v12, 1.0, v13
	v_mul_f32_e32 v13, 0xbfb8aa3b, v20
	v_mul_f32_e32 v22, 0xbfb8aa3b, v4
	v_mul_f32_e32 v23, 0xbfb8aa3b, v5
	v_mul_f32_e32 v24, 0xbfb8aa3b, v6
	v_mul_f32_e32 v25, 0xbfb8aa3b, v7
	v_mul_f32_e32 v26, 0xbfb8aa3b, v8
	v_mul_f32_e32 v27, 0xbfb8aa3b, v9
	v_mul_f32_e32 v28, 0xbfb8aa3b, v10
	v_mul_f32_e32 v29, 0xbfb8aa3b, v11
	v_rcp_f32_e32 v38, v12
	v_add_f32_e32 v12, 1.0, v14
	v_exp_f32_e32 v13, v13
	v_mul_f32_e32 v14, 0xbfb8aa3b, v21
	v_exp_f32_e32 v22, v22
	v_exp_f32_e32 v23, v23
	v_exp_f32_e32 v24, v24
	v_exp_f32_e32 v25, v25
	v_exp_f32_e32 v26, v26
	v_exp_f32_e32 v27, v27
	v_exp_f32_e32 v28, v28
	v_exp_f32_e32 v29, v29
	v_exp_f32_e32 v14, v14
	v_rcp_f32_e32 v39, v12
	v_add_f32_e32 v12, 1.0, v13
	v_add_f32_e32 v32, 1.0, v32
	v_add_f32_e32 v33, 1.0, v33
	v_add_f32_e32 v22, 1.0, v22
	v_add_f32_e32 v23, 1.0, v23
	v_add_f32_e32 v24, 1.0, v24
	v_add_f32_e32 v25, 1.0, v25
	v_add_f32_e32 v26, 1.0, v26
	v_add_f32_e32 v27, 1.0, v27
	v_add_f32_e32 v28, 1.0, v28
	v_add_f32_e32 v29, 1.0, v29
	v_rcp_f32_e32 v40, v12
	v_add_f32_e32 v12, 1.0, v14
	v_rcp_f32_e32 v32, v32
	v_rcp_f32_e32 v33, v33
	v_rcp_f32_e32 v22, v22
	v_rcp_f32_e32 v23, v23
	v_rcp_f32_e32 v24, v24
	v_rcp_f32_e32 v25, v25
	v_rcp_f32_e32 v26, v26
	v_rcp_f32_e32 v27, v27
	v_rcp_f32_e32 v28, v28
	v_rcp_f32_e32 v29, v29
	v_rcp_f32_e32 v41, v12
	v_pk_mul_f32 v[18:19], v[2:3], v[32:33]
	v_pk_mul_f32 v[16:17], v[4:5], v[22:23]
	v_pk_mul_f32 v[14:15], v[6:7], v[24:25]
	v_pk_mul_f32 v[12:13], v[8:9], v[26:27]
	v_pk_mul_f32 v[10:11], v[10:11], v[28:29]
	v_pk_mul_f32 v[8:9], v[30:31], v[34:35]
	v_pk_mul_f32 v[6:7], v[36:37], v[38:39]
	v_pk_mul_f32 v[2:3], v[20:21], v[40:41]
	s_branch .LBB0_1008
.Lfc2_entry:
	v_or3_b32 v122, v134, v114, s72
	v_cmp_gt_i32_e32 vcc, 3, v124
	s_and_saveexec_b64 s[4:5], vcc
	s_xor_b64 s[4:5], exec, s[4:5]
	s_cbranch_execz .Lfc2_1013
	v_mov_b32_e32 v5, 0
	v_mov_b32_e32 v4, 0
	v_mov_b32_e32 v3, 0
	v_mov_b32_e32 v2, 0
	v_mov_b32_e32 v13, 0
	v_mov_b32_e32 v12, 0
	v_mov_b32_e32 v11, 0
	v_mov_b32_e32 v10, 0
	v_mov_b32_e32 v9, 0
	v_mov_b32_e32 v8, 0
	v_mov_b32_e32 v7, 0
	v_mov_b32_e32 v6, 0
	v_mov_b32_e32 v17, 0
	v_mov_b32_e32 v16, 0
	v_mov_b32_e32 v15, 0
	v_mov_b32_e32 v14, 0
	s_and_saveexec_b64 s[22:23], s[6:7]
	s_cbranch_execz .Lfc2_1012
	s_load_dwordx2 s[24:25], s[18:19], 0x40
	v_ashrrev_i32_e32 v125, 31, v124
	v_lshl_add_u64 v[2:3], v[120:121], 0, v[124:125]
	s_waitcnt lgkmcnt(0)
	v_mov_b64_e32 v[4:5], s[24:25]
	v_mad_u64_u32 v[4:5], s[24:25], v2, s69, v[4:5]
	v_mov_b32_e32 v2, v5
	v_mad_u64_u32 v[2:3], s[24:25], v3, s69, v[2:3]
	v_mov_b32_e32 v5, v2
	v_lshlrev_b32_e32 v2, 2, v122
	v_mov_b32_e32 v3, v0
	v_lshl_add_u64 v[2:3], v[4:5], 0, v[2:3]
	global_load_dwordx4 v[14:17], v[2:3], off
	global_load_dwordx4 v[6:9], v[2:3], off offset:16
	global_load_dwordx4 v[10:13], v[2:3], off offset:32
	s_nop 0
	global_load_dwordx4 v[2:5], v[2:3], off offset:48

; __device__ __forceinline__ void unpack8(u32x4 v, float* f) { f[0] = bflo(v[0]); f[1] = bfhi(v[0]); f[2] = bflo(v[1]); f[3] = bfhi(v[1]); f[4] = bflo(v[2]); f[5] = bfhi(v[2]); f[6] = bflo(v[3]); f[7] = bfhi(v[3]); }
; __device__ __forceinline__ void dn_prep_unit(int layer, int sample, int b, int n, int h, unsigned char* shm) {
;     ...
;             if (tt < rows) {
; #pragma unroll
;                 for (int j = 0; j < 4; ++j) { const int lt = n * 64 + tt - 3 + j; float x[16];
;                     if (lt >= 0) { const bf16_t* s = P + (tokb + lt) * NINP + C_DQ + ch; unpack8(*(const u32x4*)s, x); unpack8(*(const u32x4*)(s + 8), x + 8); }
.Lfc2_1013:
	s_andn2_saveexec_b64 s[4:5], s[4:5]
	s_cbranch_execz .Lfc2_1015
	v_mov_b32_e32 v127, v0
	s_waitcnt vmcnt(0)
	v_lshl_add_u64 v[2:3], v[118:119], 0, v[126:127]
	v_mov_b64_e32 v[4:5], s[16:17]
	v_mad_u64_u32 v[4:5], s[22:23], v2, s68, v[4:5]
	v_mov_b32_e32 v2, v5
	v_mad_u64_u32 v[2:3], s[22:23], v3, s68, v[2:3]
	v_mov_b32_e32 v5, v2
	v_lshlrev_b32_e32 v2, 1, v122
	v_mov_b32_e32 v3, v0
	v_lshl_add_u64 v[6:7], v[4:5], 0, v[2:3]
	v_add_co_u32_e32 v2, vcc, s97, v6
	s_mov_b64 s[22:23], 0x1000
	s_nop 0
	v_addc_co_u32_e32 v3, vcc, 0, v7, vcc
	v_lshl_add_u64 v[6:7], v[6:7], 0, s[22:23]
	global_load_dwordx4 v[2:5], v[2:3], off
	s_nop 0
	global_load_dwordx4 v[18:21], v[6:7], off offset:16
	v_add_u32_e32 v34, -2, v124
	v_mov_b32_e32 v35, v0
	v_lshl_add_u64 v[34:35], v[118:119], 0, v[34:35]
	v_mov_b64_e32 v[36:37], s[16:17]
	v_mad_u64_u32 v[36:37], s[22:23], v34, s68, v[36:37]
	v_mov_b32_e32 v34, v37
	v_mad_u64_u32 v[34:35], s[22:23], v35, s68, v[34:35]
	v_mov_b32_e32 v37, v34
	v_lshlrev_b32_e32 v34, 1, v122
	v_mov_b32_e32 v35, v0
	v_lshl_add_u64 v[38:39], v[36:37], 0, v[34:35]
	v_add_co_u32_e32 v34, vcc, s97, v38
	s_mov_b64 s[22:23], 0x1000
	s_nop 0
	v_addc_co_u32_e32 v35, vcc, 0, v39, vcc
	v_lshl_add_u64 v[38:39], v[38:39], 0, s[22:23]
	global_load_dwordx4 v[34:37], v[34:35], off
	s_nop 0
	global_load_dwordx4 v[50:53], v[38:39], off offset:16
	v_add_u32_e32 v66, -1, v124
	v_mov_b32_e32 v67, v0
	v_lshl_add_u64 v[66:67], v[118:119], 0, v[66:67]
	v_mov_b64_e32 v[68:69], s[16:17]
	v_mad_u64_u32 v[68:69], s[22:23], v66, s68, v[68:69]
	v_mov_b32_e32 v66, v69
	v_mad_u64_u32 v[66:67], s[22:23], v67, s68, v[66:67]
	v_mov_b32_e32 v69, v66
	v_lshlrev_b32_e32 v66, 1, v122
	v_mov_b32_e32 v67, v0
	v_lshl_add_u64 v[70:71], v[68:69], 0, v[66:67]
	v_add_co_u32_e32 v66, vcc, s97, v70
	s_mov_b64 s[22:23], 0x1000
	s_nop 0
	v_addc_co_u32_e32 v67, vcc, 0, v71, vcc
	v_lshl_add_u64 v[70:71], v[70:71], 0, s[22:23]
	global_load_dwordx4 v[66:69], v[66:67], off
	s_nop 0
	global_load_dwordx4 v[82:85], v[70:71], off offset:16
	v_mov_b32_e32 v125, v0
	v_lshl_add_u64 v[184:185], v[118:119], 0, v[124:125]
	v_mov_b64_e32 v[186:187], s[16:17]
	v_mad_u64_u32 v[186:187], s[22:23], v184, s68, v[186:187]
	v_mov_b32_e32 v184, v187
	v_mad_u64_u32 v[184:185], s[22:23], v185, s68, v[184:185]
	v_mov_b32_e32 v187, v184
	v_lshlrev_b32_e32 v184, 1, v122
	v_mov_b32_e32 v185, v0
	v_lshl_add_u64 v[188:189], v[186:187], 0, v[184:185]
	v_add_co_u32_e32 v184, vcc, s97, v188
	s_mov_b64 s[22:23], 0x1000
	s_nop 0
	v_addc_co_u32_e32 v185, vcc, 0, v189, vcc
	v_lshl_add_u64 v[188:189], v[188:189], 0, s[22:23]
	global_load_dwordx4 v[184:187], v[184:185], off
	s_nop 0
	global_load_dwordx4 v[190:193], v[188:189], off offset:16
	s_waitcnt vmcnt(1)
	v_lshlrev_b32_e32 v14, 16, v2
	v_and_b32_e32 v15, 0xffff0000, v2
	v_lshlrev_b32_e32 v16, 16, v3
	v_and_b32_e32 v17, 0xffff0000, v3
	v_lshlrev_b32_e32 v6, 16, v4
	v_and_b32_e32 v7, 0xffff0000, v4
	v_lshlrev_b32_e32 v8, 16, v5
	v_and_b32_e32 v9, 0xffff0000, v5
	s_waitcnt vmcnt(0)
	v_lshlrev_b32_e32 v10, 16, v18
	v_and_b32_e32 v11, 0xffff0000, v18
	v_lshlrev_b32_e32 v12, 16, v19
	v_and_b32_e32 v13, 0xffff0000, v19
	v_lshlrev_b32_e32 v2, 16, v20
	v_and_b32_e32 v3, 0xffff0000, v20
	v_lshlrev_b32_e32 v4, 16, v21
	v_and_b32_e32 v5, 0xffff0000, v21

; __device__ __forceinline__ void unpack8(u32x4 v, float* f) { f[0] = bflo(v[0]); f[1] = bfhi(v[0]); f[2] = bflo(v[1]); f[3] = bfhi(v[1]); f[4] = bflo(v[2]); f[5] = bfhi(v[2]); f[6] = bflo(v[3]); f[7] = bfhi(v[3]); }
; __device__ __forceinline__ void dn_prep_unit(int layer, int sample, int b, int n, int h, unsigned char* shm) {
;     ...
;                 for (int j = 0; j < 4; ++j) { const int lt = n * 64 + tt - 3 + j; float x[16];
;                     if (lt >= 0) { const bf16_t* s = P + (tokb + lt) * NINP + C_DQ + ch; unpack8(*(const u32x4*)s, x); unpack8(*(const u32x4*)(s + 8), x + 8); }
.Lfc2_1019:
	s_andn2_saveexec_b64 s[4:5], s[4:5]
	s_cbranch_execz .Lfc2_1021
	s_waitcnt vmcnt(0)
	s_waitcnt vmcnt(1)
	v_lshlrev_b32_e32 v46, 16, v34
	v_and_b32_e32 v47, 0xffff0000, v34
	v_lshlrev_b32_e32 v48, 16, v35
	v_and_b32_e32 v49, 0xffff0000, v35
	v_lshlrev_b32_e32 v38, 16, v36
	v_and_b32_e32 v39, 0xffff0000, v36
	v_lshlrev_b32_e32 v40, 16, v37
	v_and_b32_e32 v41, 0xffff0000, v37
	s_waitcnt vmcnt(0)
	v_lshlrev_b32_e32 v42, 16, v50
	v_and_b32_e32 v43, 0xffff0000, v50
	v_lshlrev_b32_e32 v44, 16, v51
	v_and_b32_e32 v45, 0xffff0000, v51
	v_lshlrev_b32_e32 v34, 16, v52
	v_and_b32_e32 v35, 0xffff0000, v52
	v_lshlrev_b32_e32 v36, 16, v53
	v_and_b32_e32 v37, 0xffff0000, v53

; __device__ __forceinline__ void unpack8(u32x4 v, float* f) { f[0] = bflo(v[0]); f[1] = bfhi(v[0]); f[2] = bflo(v[1]); f[3] = bfhi(v[1]); f[4] = bflo(v[2]); f[5] = bfhi(v[2]); f[6] = bflo(v[3]); f[7] = bfhi(v[3]); }
; __device__ __forceinline__ void dn_prep_unit(int layer, int sample, int b, int n, int h, unsigned char* shm) {
;     ...
;                 for (int j = 0; j < 4; ++j) { const int lt = n * 64 + tt - 3 + j; float x[16];
;                     if (lt >= 0) { const bf16_t* s = P + (tokb + lt) * NINP + C_DQ + ch; unpack8(*(const u32x4*)s, x); unpack8(*(const u32x4*)(s + 8), x + 8); }
.Lfc2_1025:
	s_andn2_saveexec_b64 s[4:5], s[4:5]
	s_cbranch_execz .Lfc2_1027
	s_waitcnt vmcnt(0)
	s_waitcnt vmcnt(1)
	v_lshlrev_b32_e32 v78, 16, v66
	v_and_b32_e32 v79, 0xffff0000, v66
	v_lshlrev_b32_e32 v80, 16, v67
	v_and_b32_e32 v81, 0xffff0000, v67
	v_lshlrev_b32_e32 v74, 16, v68
	v_and_b32_e32 v75, 0xffff0000, v68
	v_lshlrev_b32_e32 v76, 16, v69
	v_and_b32_e32 v77, 0xffff0000, v69
	s_waitcnt vmcnt(0)
	v_lshlrev_b32_e32 v70, 16, v82
	v_and_b32_e32 v71, 0xffff0000, v82
	v_lshlrev_b32_e32 v72, 16, v83
	v_and_b32_e32 v73, 0xffff0000, v83
	v_lshlrev_b32_e32 v66, 16, v84
	v_and_b32_e32 v67, 0xffff0000, v84
	v_lshlrev_b32_e32 v68, 16, v85
	v_and_b32_e32 v69, 0xffff0000, v85

; __device__ __forceinline__ float siluf_(float x) { return x * __builtin_amdgcn_rcpf(1.0f + __expf(-x)); }
; __device__ __forceinline__ void dn_prep_unit(int layer, int sample, int b, int n, int h, unsigned char* shm) {
;     ...
;                     const float* w = WL + (sel * 4 + j) * 128 + part * 16;
; #pragma unroll
;                     for (int i = 0; i < 16; ++i) y[i] += x[i] * w[i]; }
; #pragma unroll
;                 for (int i = 0; i < 16; ++i) y[i] = siluf_(y[i]);
.Lfc2_1031:
	s_andn2_saveexec_b64 s[4:5], s[4:5]
	s_cbranch_execz .Lfc2_1033
	v_mov_b32_e32 v125, v0
	s_waitcnt vmcnt(0)
	s_waitcnt vmcnt(1)
	v_lshlrev_b32_e32 v110, 16, v184
	v_and_b32_e32 v111, 0xffff0000, v184
	v_lshlrev_b32_e32 v112, 16, v185
	v_and_b32_e32 v113, 0xffff0000, v185
	v_lshlrev_b32_e32 v102, 16, v186
	v_and_b32_e32 v103, 0xffff0000, v186
	v_lshlrev_b32_e32 v104, 16, v187
	v_and_b32_e32 v105, 0xffff0000, v187
	s_waitcnt vmcnt(0)
	v_lshlrev_b32_e32 v86, 16, v190
	v_and_b32_e32 v87, 0xffff0000, v190
	v_lshlrev_b32_e32 v88, 16, v191
	v_and_b32_e32 v89, 0xffff0000, v191
	v_lshlrev_b32_e32 v82, 16, v192
	v_and_b32_e32 v83, 0xffff0000, v192
	v_lshlrev_b32_e32 v84, 16, v193
	v_and_b32_e32 v85, 0xffff0000, v193
.Lfc2_1033:
	s_or_b64 exec, exec, s[4:5]
	s_waitcnt vmcnt(0) lgkmcnt(8)
	v_pk_fma_f32 v[2:3], v[2:3], v[18:19], 0 op_sel_hi:[1,1,0]
	v_pk_fma_f32 v[4:5], v[4:5], v[20:21], 0 op_sel_hi:[1,1,0]
	s_waitcnt lgkmcnt(4)
	v_pk_fma_f32 v[18:19], v[34:35], v[50:51], v[2:3]
	v_pk_fma_f32 v[20:21], v[36:37], v[52:53], v[4:5]
	ds_read_b128 v[2:5], v129 offset:5632
	v_pk_fma_f32 v[14:15], v[14:15], v[30:31], 0 op_sel_hi:[1,1,0]
	v_pk_fma_f32 v[6:7], v[6:7], v[26:27], 0 op_sel_hi:[1,1,0]
	v_pk_fma_f32 v[8:9], v[8:9], v[28:29], 0 op_sel_hi:[1,1,0]
	v_pk_fma_f32 v[14:15], v[46:47], v[62:63], v[14:15]
	v_pk_fma_f32 v[10:11], v[10:11], v[22:23], 0 op_sel_hi:[1,1,0]
	v_pk_fma_f32 v[6:7], v[38:39], v[58:59], v[6:7]
	v_pk_fma_f32 v[8:9], v[40:41], v[60:61], v[8:9]
	s_waitcnt lgkmcnt(4)
	v_pk_fma_f32 v[14:15], v[78:79], v[106:107], v[14:15]
	v_pk_fma_f32 v[12:13], v[12:13], v[24:25], 0 op_sel_hi:[1,1,0]
	v_pk_fma_f32 v[10:11], v[42:43], v[54:55], v[10:11]
	s_waitcnt lgkmcnt(3)
	v_pk_fma_f32 v[24:25], v[74:75], v[98:99], v[6:7]
	v_pk_fma_f32 v[26:27], v[76:77], v[100:101], v[8:9]
	ds_read_b128 v[6:9], v129 offset:5648
	s_waitcnt lgkmcnt(1)
	v_pk_fma_f32 v[2:3], v[110:111], v[2:3], v[14:15]
	v_pk_fma_f32 v[16:17], v[16:17], v[32:33], 0 op_sel_hi:[1,1,0]
	v_pk_fma_f32 v[28:29], v[70:71], v[94:95], v[10:11]
	v_mul_f32_e32 v10, 0xbfb8aa3b, v2
	v_pk_fma_f32 v[16:17], v[48:49], v[64:65], v[16:17]
	v_pk_fma_f32 v[12:13], v[44:45], v[56:57], v[12:13]
	v_exp_f32_e32 v32, v10
	v_mul_f32_e32 v10, 0xbfb8aa3b, v3
	v_pk_fma_f32 v[22:23], v[80:81], v[108:109], v[16:17]
	v_pk_fma_f32 v[30:31], v[72:73], v[96:97], v[12:13]
	v_exp_f32_e32 v33, v10
	ds_read_b128 v[10:13], v129 offset:5664
	ds_read_b128 v[14:17], v129 offset:5680
	v_pk_fma_f32 v[18:19], v[66:67], v[90:91], v[18:19]
	v_pk_fma_f32 v[20:21], v[68:69], v[92:93], v[20:21]
	v_pk_fma_f32 v[4:5], v[112:113], v[4:5], v[22:23]
	s_waitcnt lgkmcnt(1)
	v_pk_fma_f32 v[28:29], v[86:87], v[10:11], v[28:29]
	v_pk_fma_f32 v[30:31], v[88:89], v[12:13], v[30:31]
	v_mul_f32_e32 v10, 0xbfb8aa3b, v28
	v_exp_f32_e32 v10, v10
	v_mul_f32_e32 v11, 0xbfb8aa3b, v29
	v_exp_f32_e32 v11, v11
	v_mul_f32_e32 v12, 0xbfb8aa3b, v31
	v_add_f32_e32 v10, 1.0, v10
	v_rcp_f32_e32 v34, v10
	v_add_f32_e32 v10, 1.0, v11
	v_mul_f32_e32 v11, 0xbfb8aa3b, v30
	v_exp_f32_e32 v11, v11
	v_exp_f32_e32 v12, v12
	s_waitcnt lgkmcnt(0)
	v_pk_fma_f32 v[18:19], v[82:83], v[14:15], v[18:19]
	v_rcp_f32_e32 v35, v10
	v_add_f32_e32 v10, 1.0, v11
	v_mul_f32_e32 v11, 0xbfb8aa3b, v18
	v_rcp_f32_e32 v36, v10
	v_add_f32_e32 v10, 1.0, v12
	v_exp_f32_e32 v11, v11
	v_mul_f32_e32 v12, 0xbfb8aa3b, v19
	v_exp_f32_e32 v12, v12
	v_pk_fma_f32 v[20:21], v[84:85], v[16:17], v[20:21]
	v_pk_fma_f32 v[6:7], v[102:103], v[6:7], v[24:25]
	v_pk_fma_f32 v[8:9], v[104:105], v[8:9], v[26:27]
	v_rcp_f32_e32 v37, v10
	v_add_f32_e32 v10, 1.0, v11
	v_mul_f32_e32 v11, 0xbfb8aa3b, v20
	v_mul_f32_e32 v22, 0xbfb8aa3b, v4
	v_mul_f32_e32 v23, 0xbfb8aa3b, v5
	v_mul_f32_e32 v24, 0xbfb8aa3b, v6
	v_mul_f32_e32 v25, 0xbfb8aa3b, v7
	v_mul_f32_e32 v26, 0xbfb8aa3b, v8
	v_mul_f32_e32 v27, 0xbfb8aa3b, v9
	v_rcp_f32_e32 v38, v10
	v_add_f32_e32 v10, 1.0, v12
	v_exp_f32_e32 v11, v11
	v_mul_f32_e32 v12, 0xbfb8aa3b, v21
	v_exp_f32_e32 v22, v22
	v_exp_f32_e32 v23, v23
	v_exp_f32_e32 v24, v24
	v_exp_f32_e32 v25, v25
	v_exp_f32_e32 v26, v26
	v_exp_f32_e32 v27, v27
	v_exp_f32_e32 v12, v12
	v_rcp_f32_e32 v39, v10
	v_add_f32_e32 v10, 1.0, v11
	v_add_f32_e32 v32, 1.0, v32
	v_add_f32_e32 v33, 1.0, v33
	v_add_f32_e32 v22, 1.0, v22
	v_add_f32_e32 v23, 1.0, v23
	v_add_f32_e32 v24, 1.0, v24
	v_add_f32_e32 v25, 1.0, v25
	v_add_f32_e32 v26, 1.0, v26
	v_add_f32_e32 v27, 1.0, v27
	v_rcp_f32_e32 v40, v10
	v_add_f32_e32 v10, 1.0, v12
	v_rcp_f32_e32 v32, v32
	v_rcp_f32_e32 v33, v33
	v_rcp_f32_e32 v22, v22
	v_rcp_f32_e32 v23, v23
	v_rcp_f32_e32 v24, v24
	v_rcp_f32_e32 v25, v25
	v_rcp_f32_e32 v26, v26
	v_rcp_f32_e32 v27, v27
	v_rcp_f32_e32 v41, v10
	v_pk_mul_f32 v[16:17], v[2:3], v[32:33]
	v_pk_mul_f32 v[14:15], v[4:5], v[22:23]
	v_pk_mul_f32 v[12:13], v[6:7], v[24:25]
	v_pk_mul_f32 v[10:11], v[8:9], v[26:27]
	v_pk_mul_f32 v[8:9], v[28:29], v[34:35]
	v_pk_mul_f32 v[6:7], v[30:31], v[36:37]
	v_pk_mul_f32 v[2:3], v[18:19], v[38:39]
	v_pk_mul_f32 v[4:5], v[20:21], v[40:41]
	s_branch .LBB0_1034

; __device__ __forceinline__ void unpack8(u32x4 v, float* f) { f[0] = bflo(v[0]); f[1] = bfhi(v[0]); f[2] = bflo(v[1]); f[3] = bfhi(v[1]); f[4] = bflo(v[2]); f[5] = bfhi(v[2]); f[6] = bflo(v[3]); f[7] = bfhi(v[3]); }
; __device__ __forceinline__ void dn_prep_unit(int layer, int sample, int b, int n, int h, unsigned char* shm) {
;     ...
;     {
;         const int tt = tid >> 3, part = tid & 7; const float gc = gcum[tt], bt = beta[tt], glast = gcum[63];
;         const float eg = expf(gc), ekd = expf(glast - gc);
; #pragma unroll
;         for (int sel = 0; sel < 3; ++sel) {
;             const int ch = sel * 1024 + h * 128 + part * 16; float y[16];
; #pragma unroll
;             for (int i = 0; i < 16; ++i) y[i] = 0.f;
;             if (tt < rows) {
; #pragma unroll
;                 for (int j = 0; j < 4; ++j) { const int lt = n * 64 + tt - 3 + j; float x[16];
;                     if (lt >= 0) { const bf16_t* s = P + (tokb + lt) * NINP + C_DQ + ch; unpack8(*(const u32x4*)s, x); unpack8(*(const u32x4*)(s + 8), x + 8); }
.LBB0_956:
	s_or_b64 exec, exec, s[20:21]
	v_ashrrev_i32_e32 v135, 3, v146
	v_lshl_add_u32 v3, v135, 2, 0
	s_waitcnt lgkmcnt(0)
	s_barrier
	ds_read2st64_b32 v[122:123], v3 offset1:1
	ds_read_b32 v136, v0 offset:252
	v_lshlrev_b32_e32 v3, 4, v146
	v_and_b32_e32 v134, 0x70, v3
	v_cmp_lt_i32_e64 s[4:5], v135, v2
	v_readlane_b32 s20, v254, 18
	v_lshl_add_u64 v[2:3], s[30:31], 0, v[116:117]
	v_lshl_add_u32 v124, v1, 6, v135
	v_lshl_add_u32 v129, v134, 2, s20
	v_mad_u64_u32 v[120:121], s[20:21], v2, 3, 0
	v_add_u32_e32 v126, -3, v124
	v_mad_i32_i24 v121, v3, 3, v121
	v_mov_b32_e32 v19, 0
	v_mov_b32_e32 v18, 0
	v_mov_b32_e32 v17, 0
	v_mov_b32_e32 v16, 0
	v_mov_b32_e32 v15, 0
	v_mov_b32_e32 v14, 0
	v_mov_b32_e32 v13, 0
	v_mov_b32_e32 v12, 0
	v_mov_b32_e32 v11, 0
	v_mov_b32_e32 v10, 0
	v_mov_b32_e32 v9, 0
	v_mov_b32_e32 v8, 0
	v_mov_b32_e32 v7, 0
	v_mov_b32_e32 v6, 0
	v_mov_b32_e32 v5, 0
	v_mov_b32_e32 v4, 0
	s_and_saveexec_b64 s[20:21], s[4:5]
	s_cbranch_execz .LBB0_982
	v_readfirstlane_b32 s98, v124
	s_nop 0
	s_cmpk_ge_i32 s98, 0x40
	s_cbranch_scc1 .Lfc0_entry
	v_or_b32_e32 v128, v134, v114
	v_cmp_gt_i32_e32 vcc, 3, v124
	s_and_saveexec_b64 s[22:23], vcc
	s_xor_b64 s[22:23], exec, s[22:23]
	s_cbranch_execz .LBB0_961
	v_mov_b32_e32 v5, 0
	v_mov_b32_e32 v4, 0
	v_mov_b32_e32 v3, 0
	v_mov_b32_e32 v2, 0
	v_mov_b32_e32 v13, 0
	v_mov_b32_e32 v12, 0
	v_mov_b32_e32 v11, 0
	v_mov_b32_e32 v10, 0
	v_mov_b32_e32 v9, 0
	v_mov_b32_e32 v8, 0
	v_mov_b32_e32 v7, 0
	v_mov_b32_e32 v6, 0
	v_mov_b32_e32 v17, 0
	v_mov_b32_e32 v16, 0
	v_mov_b32_e32 v15, 0
	v_mov_b32_e32 v14, 0
	s_and_saveexec_b64 s[24:25], s[6:7]
	s_cbranch_execz .LBB0_960
	s_load_dwordx2 s[38:39], s[18:19], 0x40
	v_ashrrev_i32_e32 v125, 31, v124
	v_lshl_add_u64 v[2:3], v[120:121], 0, v[124:125]
	s_waitcnt lgkmcnt(0)
	v_mov_b64_e32 v[4:5], s[38:39]
	v_mad_u64_u32 v[4:5], s[38:39], v2, s69, v[4:5]
	v_mov_b32_e32 v2, v5
	v_mad_u64_u32 v[2:3], s[38:39], v3, s69, v[2:3]
	v_mov_b32_e32 v5, v2
	v_lshlrev_b32_e32 v2, 2, v128
	v_mov_b32_e32 v3, v0
	v_lshl_add_u64 v[2:3], v[4:5], 0, v[2:3]
	global_load_dwordx4 v[14:17], v[2:3], off
	global_load_dwordx4 v[6:9], v[2:3], off offset:16
	global_load_dwordx4 v[10:13], v[2:3], off offset:32
	s_nop 0
	global_load_dwordx4 v[2:5], v[2:3], off offset:48

; __device__ __forceinline__ void unpack8(u32x4 v, float* f) { f[0] = bflo(v[0]); f[1] = bfhi(v[0]); f[2] = bflo(v[1]); f[3] = bfhi(v[1]); f[4] = bflo(v[2]); f[5] = bfhi(v[2]); f[6] = bflo(v[3]); f[7] = bfhi(v[3]); }
; __device__ __forceinline__ u32x4 pack8(const float* f) { u32x4 r; r[0] = cvt_pk_bf16(f[0], f[1]); r[1] = cvt_pk_bf16(f[2], f[3]); r[2] = cvt_pk_bf16(f[4], f[5]); r[3] = cvt_pk_bf16(f[6], f[7]); return r; }
; __device__ __forceinline__ void dn_prep_unit(int layer, int sample, int b, int n, int h, unsigned char* shm) {
;     ...
;             if (tt < rows) {
; #pragma unroll
;                 for (int j = 0; j < 4; ++j) { const int lt = n * 64 + tt - 3 + j; float x[16];
;                     if (lt >= 0) { const bf16_t* s = P + (tokb + lt) * NINP + C_DQ + ch; unpack8(*(const u32x4*)s, x); unpack8(*(const u32x4*)(s + 8), x + 8); }
;     ...
;             if (sel < 2) { float ss = 0.f;
; #pragma unroll
;                 for (int i = 0; i < 16; ++i) ss += y[i] * y[i];
;                 ss += __shfl_xor(ss, 1); ss += __shfl_xor(ss, 2); ss += __shfl_xor(ss, 4);
;                 const float rs = rsqrtf(ss + 1e-6f);
; #pragma unroll
;                 for (int i = 0; i < 16; ++i) y[i] *= rs; }
;             if (sel == 0) { float t[16];
; #pragma unroll
;                 for (int i = 0; i < 16; ++i) t[i] = y[i] * 0.08838834764831845f;
;                 *(u32x4*)(Q16 + tt * 136 + part * 16) = pack8(t); *(u32x4*)(Q16 + tt * 136 + part * 16 + 8) = pack8(t + 8);
; #pragma unroll
;                 for (int i = 0; i < 16; ++i) t[i] *= eg;
;                 *(u32x4*)(QGg + tt * 128 + part * 16) = pack8(t); *(u32x4*)(QGg + tt * 128 + part * 16 + 8) = pack8(t + 8);
.LBB0_982:
	s_or_b64 exec, exec, s[20:21]
	v_mul_f32_e32 v28, v5, v5
	v_fmac_f32_e32 v28, v4, v4
	v_fmac_f32_e32 v28, v6, v6
	v_fmac_f32_e32 v28, v7, v7
	v_fmac_f32_e32 v28, v8, v8
	v_fmac_f32_e32 v28, v9, v9
	v_fmac_f32_e32 v28, v10, v10
	s_waitcnt lgkmcnt(1)
	v_mul_f32_e32 v2, 0x3fb8aa3b, v122
	v_fmac_f32_e32 v28, v11, v11
	v_pk_mul_f32 v[24:25], v[12:13], v[12:13]
	v_rndne_f32_e32 v3, v2
	s_mov_b32 s20, 0x3fb8aa3b
	v_add_f32_e32 v24, v24, v28
	v_sub_f32_e32 v20, v2, v3
	v_fma_f32 v2, v122, s20, -v2
	v_pk_mul_f32 v[22:23], v[14:15], v[14:15]
	v_add_f32_e32 v24, v25, v24
	v_fmac_f32_e32 v2, 0x32a5705f, v122
	v_add_f32_e32 v22, v22, v24
	v_add_f32_e32 v2, v20, v2
	v_pk_mul_f32 v[20:21], v[16:17], v[16:17]
	v_add_f32_e32 v22, v23, v22
	v_add_f32_e32 v20, v20, v22
	v_exp_f32_e32 v26, v2
	v_cvt_i32_f32_e32 v27, v3
	v_pk_mul_f32 v[2:3], v[18:19], v[18:19]
	v_add_f32_e32 v20, v21, v20
	v_add_f32_e32 v2, v2, v20
	v_and_b32_e32 v20, 64, v227
	v_add_f32_e32 v2, v3, v2
	v_xor_b32_e32 v3, 1, v227
	v_add_u32_e32 v20, 64, v20
	v_cmp_lt_i32_e32 vcc, v3, v20
	s_mov_b32 s20, 0xc2ce8ed0
	v_ldexp_f32 v22, v26, v27
	v_cndmask_b32_e32 v3, v227, v3, vcc
	v_lshlrev_b32_e32 v138, 2, v3
	ds_bpermute_b32 v21, v138, v2
	v_lshlrev_b32_e32 v130, 1, v134
	v_mov_b32_e32 v131, v0
	v_mul_lo_u32 v137, v135, s95
	v_mov_b32_e32 v3, 0
	s_waitcnt lgkmcnt(0)
	v_add_f32_e32 v2, v2, v21
	v_xor_b32_e32 v21, 2, v227
	v_cmp_lt_i32_e32 vcc, v21, v20
	s_nop 1
	v_cndmask_b32_e32 v21, v227, v21, vcc
	v_lshlrev_b32_e32 v139, 2, v21
	ds_bpermute_b32 v21, v139, v2
	v_cmp_ngt_f32_e32 vcc, s20, v122
	s_mov_b32 s20, 0x42b17218
	s_waitcnt lgkmcnt(0)
	v_add_f32_e32 v2, v2, v21
	v_cndmask_b32_e32 v22, 0, v22, vcc
	v_cmp_nlt_f32_e32 vcc, s20, v122
	v_xor_b32_e32 v21, 4, v227
	s_mov_b64 s[20:21], 0xc000
	v_cndmask_b32_e32 v128, v225, v22, vcc
	v_cmp_lt_i32_e32 vcc, v21, v20
	s_nop 1
	v_cndmask_b32_e32 v20, v227, v21, vcc
	v_lshlrev_b32_e32 v140, 2, v20
	ds_bpermute_b32 v22, v140, v2
	v_lshlrev_b32_e32 v20, 7, v135
	v_ashrrev_i32_e32 v21, 31, v20
	v_lshl_add_u64 v[132:133], v[20:21], 1, v[148:149]
	s_waitcnt lgkmcnt(0)
	v_add_f32_e32 v2, v2, v22
	v_add_f32_e32 v2, 0x358637bd, v2
	v_mul_f32_e32 v20, 0x4b800000, v2
	v_cmp_gt_f32_e32 vcc, s91, v2
	s_nop 1
	v_cndmask_b32_e32 v2, v2, v20, vcc
	v_rsq_f32_e32 v2, v2
	v_lshl_add_u64 v[20:21], v[132:133], 0, v[130:131]
	v_lshl_add_u64 v[22:23], v[20:21], 0, s[20:21]
	v_readlane_b32 s20, v254, 19
	v_mul_f32_e32 v24, 0x45800000, v2
	v_cndmask_b32_e32 v2, v2, v24, vcc
	v_mul_f32_e32 v11, v11, v2
	v_mul_f32_e32 v10, v10, v2
	v_mul_f32_e32 v9, v9, v2
	v_mul_f32_e32 v8, v8, v2
	v_mul_f32_e32 v7, v7, v2
	v_mul_f32_e32 v6, v6, v2
	v_mul_f32_e32 v5, v5, v2
	v_mul_f32_e32 v19, v19, v2
	v_mul_f32_e32 v18, v18, v2
	v_mul_f32_e32 v17, v17, v2
	v_mul_f32_e32 v16, v16, v2
	v_mul_f32_e32 v15, v15, v2
	v_mul_f32_e32 v14, v14, v2
	v_mul_f32_e32 v13, v13, v2
	v_mul_f32_e32 v12, v12, v2
	v_mul_f32_e32 v2, v4, v2
	v_mul_f32_e32 v24, 0x3db504f3, v5
	v_mul_f32_e32 v25, 0x3db504f3, v6
	v_mul_f32_e32 v26, 0x3db504f3, v7
	v_mul_f32_e32 v8, 0x3db504f3, v8
	v_mul_f32_e32 v9, 0x3db504f3, v9
	v_mul_f32_e32 v10, 0x3db504f3, v10
	v_mul_f32_e32 v11, 0x3db504f3, v11
	v_cvt_pk_bf16_f32 v5, v25, v26
	v_cvt_pk_bf16_f32 v6, v8, v9
	v_cvt_pk_bf16_f32 v7, v10, v11
	v_add3_u32 v27, s20, v130, v137
	v_mul_f32_e32 v2, 0x3db504f3, v2
	v_mul_f32_e32 v14, 0x3db504f3, v14
	v_mul_f32_e32 v15, 0x3db504f3, v15
	v_mul_f32_e32 v16, 0x3db504f3, v16
	v_mul_f32_e32 v17, 0x3db504f3, v17
	v_mul_f32_e32 v18, 0x3db504f3, v18
	v_mul_f32_e32 v19, 0x3db504f3, v19
	v_cvt_pk_bf16_f32 v4, v2, v24
	ds_write_b128 v27, v[4:7]
	v_cvt_pk_bf16_f32 v5, v14, v15
	v_cvt_pk_bf16_f32 v6, v16, v17
	v_cvt_pk_bf16_f32 v7, v18, v19
	v_mul_f32_e32 v12, 0x3db504f3, v12
	v_mul_f32_e32 v13, 0x3db504f3, v13
	v_cvt_pk_bf16_f32 v4, v12, v13
	ds_write_b128 v27, v[4:7] offset:16
	v_mul_f32_e32 v5, v128, v25
	v_mul_f32_e32 v6, v128, v26
	v_mul_f32_e32 v7, v128, v8
	v_mul_f32_e32 v8, v128, v9
	v_mul_f32_e32 v9, v128, v10
	v_cvt_pk_bf16_f32 v5, v5, v6
	v_cvt_pk_bf16_f32 v6, v7, v8
	v_add_co_u32_e32 v8, vcc, 0xc000, v20
	v_mul_f32_e32 v4, v128, v24
	v_mul_f32_e32 v10, v128, v11
	v_cvt_pk_bf16_f32 v7, v9, v10
	v_addc_co_u32_e32 v9, vcc, 0, v21, vcc
	v_mul_f32_e32 v2, v128, v2
	v_mul_f32_e32 v11, v128, v12
	v_mul_f32_e32 v12, v128, v13
	v_mul_f32_e32 v13, v128, v14
	v_mul_f32_e32 v14, v128, v15
	v_mul_f32_e32 v15, v128, v16
	v_mul_f32_e32 v16, v128, v17
	v_mul_f32_e32 v17, v128, v18
	v_mul_f32_e32 v18, v128, v19
	v_cvt_pk_bf16_f32 v4, v2, v4
	global_store_dwordx4 v[8:9], v[4:7], off
	v_mov_b32_e32 v2, 0
	v_mov_b32_e32 v9, 0
	v_cvt_pk_bf16_f32 v6, v15, v16
	v_cvt_pk_bf16_f32 v7, v17, v18
	v_cvt_pk_bf16_f32 v4, v11, v12
	v_cvt_pk_bf16_f32 v5, v13, v14
	global_store_dwordx4 v[22:23], v[4:7], off offset:16
	v_mov_b32_e32 v8, 0
	v_mov_b32_e32 v11, 0
	v_mov_b32_e32 v7, 0
	v_mov_b32_e32 v6, 0
	v_mov_b32_e32 v10, 0
	v_mov_b32_e32 v13, 0
	v_mov_b32_e32 v12, 0
	v_mov_b32_e32 v15, 0
	v_mov_b32_e32 v14, 0
	v_mov_b32_e32 v17, 0
	v_mov_b32_e32 v16, 0
	v_mov_b32_e32 v19, 0
	v_mov_b32_e32 v18, 0
	s_and_saveexec_b64 s[20:21], s[4:5]
	s_cbranch_execz .LBB0_1008
	v_readfirstlane_b32 s98, v124
	s_nop 0
	s_cmpk_ge_i32 s98, 0x40
	s_cbranch_scc1 .Lfc1_entry
	v_or3_b32 v131, v134, v114, s71
	v_cmp_gt_i32_e32 vcc, 3, v124
	s_and_saveexec_b64 s[22:23], vcc
	s_xor_b64 s[22:23], exec, s[22:23]
	s_cbranch_execz .LBB0_987
	v_mov_b32_e32 v5, 0
	v_mov_b32_e32 v4, 0
	v_mov_b32_e32 v3, 0
	v_mov_b32_e32 v2, 0
	v_mov_b32_e32 v13, 0
	v_mov_b32_e32 v12, 0
	v_mov_b32_e32 v11, 0
	v_mov_b32_e32 v10, 0
	v_mov_b32_e32 v9, 0
	v_mov_b32_e32 v8, 0
	v_mov_b32_e32 v7, 0
	v_mov_b32_e32 v6, 0
	v_mov_b32_e32 v17, 0
	v_mov_b32_e32 v16, 0
	v_mov_b32_e32 v15, 0
	v_mov_b32_e32 v14, 0
	s_and_saveexec_b64 s[24:25], s[6:7]
	s_cbranch_execz .LBB0_986
	s_load_dwordx2 s[38:39], s[18:19], 0x40
	v_ashrrev_i32_e32 v125, 31, v124
	v_lshl_add_u64 v[2:3], v[120:121], 0, v[124:125]
	s_waitcnt lgkmcnt(0)
	v_mov_b64_e32 v[4:5], s[38:39]
	v_mad_u64_u32 v[4:5], s[38:39], v2, s69, v[4:5]
	v_mov_b32_e32 v2, v5
	v_mad_u64_u32 v[2:3], s[38:39], v3, s69, v[2:3]
	v_mov_b32_e32 v5, v2
	v_lshlrev_b32_e32 v2, 2, v131
	v_mov_b32_e32 v3, v0
	v_lshl_add_u64 v[2:3], v[4:5], 0, v[2:3]
	global_load_dwordx4 v[14:17], v[2:3], off
	global_load_dwordx4 v[6:9], v[2:3], off offset:16
	global_load_dwordx4 v[10:13], v[2:3], off offset:32
	s_nop 0
	global_load_dwordx4 v[2:5], v[2:3], off offset:48

; __device__ __forceinline__ void unpack8(u32x4 v, float* f) { f[0] = bflo(v[0]); f[1] = bfhi(v[0]); f[2] = bflo(v[1]); f[3] = bfhi(v[1]); f[4] = bflo(v[2]); f[5] = bfhi(v[2]); f[6] = bflo(v[3]); f[7] = bfhi(v[3]); }
; __device__ __forceinline__ u32x4 pack8(const float* f) { u32x4 r; r[0] = cvt_pk_bf16(f[0], f[1]); r[1] = cvt_pk_bf16(f[2], f[3]); r[2] = cvt_pk_bf16(f[4], f[5]); r[3] = cvt_pk_bf16(f[6], f[7]); return r; }
; __device__ __forceinline__ void dn_prep_unit(int layer, int sample, int b, int n, int h, unsigned char* shm) {
;     ...
;             if (tt < rows) {
; #pragma unroll
;                 for (int j = 0; j < 4; ++j) { const int lt = n * 64 + tt - 3 + j; float x[16];
;                     if (lt >= 0) { const bf16_t* s = P + (tokb + lt) * NINP + C_DQ + ch; unpack8(*(const u32x4*)s, x); unpack8(*(const u32x4*)(s + 8), x + 8); }
;     ...
;             } else if (sel == 1) { float t[16];
;                 *(u32x4*)(K16 + tt * 136 + part * 16) = pack8(y); *(u32x4*)(K16 + tt * 136 + part * 16 + 8) = pack8(y + 8);
; #pragma unroll
;                 for (int i = 0; i < 16; ++i) { RHS[tt * 260 + 128 + part * 16 + i] = y[i] * bt * eg; t[i] = y[i] * ekd; }
;                 *(u32x4*)(KDg + tt * 128 + part * 16) = pack8(t); *(u32x4*)(KDg + tt * 128 + part * 16 + 8) = pack8(t + 8);
.LBB0_1008:
	s_or_b64 exec, exec, s[20:21]
	v_mul_f32_e32 v30, v19, v19
	v_fmac_f32_e32 v30, v18, v18
	v_fmac_f32_e32 v30, v16, v16
	v_fmac_f32_e32 v30, v17, v17
	v_fmac_f32_e32 v30, v14, v14
	v_fmac_f32_e32 v30, v15, v15
	v_fmac_f32_e32 v30, v12, v12
	v_fmac_f32_e32 v30, v13, v13
	v_pk_mul_f32 v[24:25], v[10:11], v[10:11]
	v_pk_mul_f32 v[22:23], v[8:9], v[8:9]
	v_add_f32_e32 v24, v24, v30
	v_add_f32_e32 v24, v25, v24
	v_sub_f32_e32 v26, v136, v122
	v_add_f32_e32 v22, v22, v24
	v_mul_f32_e32 v4, 0x3fb8aa3b, v26
	v_pk_mul_f32 v[20:21], v[6:7], v[6:7]
	v_add_f32_e32 v22, v23, v22
	s_mov_b32 s20, 0x3fb8aa3b
	v_rndne_f32_e32 v28, v4
	v_add_f32_e32 v20, v20, v22
	v_fma_f32 v27, v26, s20, -v4
	v_sub_f32_e32 v29, v4, v28
	v_pk_mul_f32 v[4:5], v[2:3], v[2:3]
	v_add_f32_e32 v20, v21, v20
	v_add_f32_e32 v4, v4, v20
	v_add_f32_e32 v4, v5, v4
	ds_bpermute_b32 v5, v138, v4
	v_fmac_f32_e32 v27, 0x32a5705f, v26
	v_add_f32_e32 v20, v29, v27
	v_exp_f32_e32 v20, v20
	v_cvt_i32_f32_e32 v21, v28
	s_waitcnt lgkmcnt(0)
	v_add_f32_e32 v4, v4, v5
	ds_bpermute_b32 v22, v139, v4
	s_mov_b32 s20, 0xc2ce8ed0
	v_ldexp_f32 v20, v20, v21
	v_cmp_ngt_f32_e32 vcc, s20, v26
	s_mov_b32 s20, 0x42b17218
	s_waitcnt lgkmcnt(0)
	v_add_f32_e32 v4, v4, v22
	ds_bpermute_b32 v21, v140, v4
	v_cndmask_b32_e32 v20, 0, v20, vcc
	v_cmp_nlt_f32_e32 vcc, s20, v26
	v_mov_b32_e32 v5, 0
	v_mov_b32_e32 v131, v0
	s_waitcnt lgkmcnt(0)
	v_add_f32_e32 v4, v4, v21
	v_add_f32_e32 v4, 0x358637bd, v4
	v_cndmask_b32_e32 v31, v225, v20, vcc
	v_mul_f32_e32 v20, 0x4b800000, v4
	v_cmp_gt_f32_e32 vcc, s91, v4
	v_lshl_add_u64 v[26:27], v[132:133], 0, v[130:131]
	s_mov_b64 s[20:21], 0x10000
	v_cndmask_b32_e32 v4, v4, v20, vcc
	v_rsq_f32_e32 v4, v4
	v_mov_b32_e32 v30, v123
	v_lshl_add_u64 v[28:29], v[26:27], 0, s[20:21]
	v_readlane_b32 s20, v254, 20
	v_mul_f32_e32 v20, 0x45800000, v4
	v_cndmask_b32_e32 v4, v4, v20, vcc
	v_pk_mul_f32 v[20:21], v[18:19], v[4:5] op_sel_hi:[1,0]
	v_pk_mul_f32 v[16:17], v[16:17], v[4:5] op_sel_hi:[1,0]
	v_cvt_pk_bf16_f32 v18, v20, v21
	v_mul_f32_e32 v33, v31, v20
	v_pk_mul_f32 v[22:23], v[30:31], v[20:21] op_sel_hi:[0,1]
	v_mul_f32_e32 v34, v31, v21
	v_cvt_pk_bf16_f32 v19, v16, v17
	v_mul_f32_e32 v35, v31, v16
	v_pk_mul_f32 v[20:21], v[30:31], v[16:17] op_sel_hi:[0,1]
	v_mul_f32_e32 v36, v31, v17
	v_pk_mul_f32 v[16:17], v[14:15], v[4:5] op_sel_hi:[1,0]
	v_pk_mul_f32 v[12:13], v[12:13], v[4:5] op_sel_hi:[1,0]
	v_pk_mul_f32 v[24:25], v[128:129], v[20:21] op_sel_hi:[0,1]
	v_cvt_pk_bf16_f32 v20, v16, v17
	v_mul_f32_e32 v37, v31, v16
	v_pk_mul_f32 v[14:15], v[30:31], v[16:17] op_sel_hi:[0,1]
	v_mul_f32_e32 v38, v31, v17
	v_cvt_pk_bf16_f32 v21, v12, v13
	v_add3_u32 v39, s20, v130, v137
	v_mul_f32_e32 v40, v31, v12
	v_pk_mul_f32 v[16:17], v[30:31], v[12:13] op_sel_hi:[0,1]
	v_mul_f32_e32 v41, v31, v13
	v_pk_mul_f32 v[12:13], v[10:11], v[4:5] op_sel_hi:[1,0]
	v_pk_mul_f32 v[8:9], v[8:9], v[4:5] op_sel_hi:[1,0]
	ds_write_b128 v39, v[18:21]
	v_cvt_pk_bf16_f32 v10, v12, v13
	v_mul_f32_e32 v42, v31, v12
	v_pk_mul_f32 v[18:19], v[30:31], v[12:13] op_sel_hi:[0,1]
	v_mul_f32_e32 v43, v31, v13
	v_cvt_pk_bf16_f32 v11, v8, v9
	v_mul_f32_e32 v44, v31, v8
	v_pk_mul_f32 v[12:13], v[30:31], v[8:9] op_sel_hi:[0,1]
	v_mul_f32_e32 v45, v31, v9
	v_pk_mul_f32 v[8:9], v[6:7], v[4:5] op_sel_hi:[1,0]
	v_pk_mul_f32 v[2:3], v[2:3], v[4:5] op_sel_hi:[1,0]
	v_mul_lo_u32 v135, v135, s59
	v_lshlrev_b32_e32 v136, 2, v134
	v_pk_mul_f32 v[20:21], v[128:129], v[12:13] op_sel_hi:[0,1]
	v_cvt_pk_bf16_f32 v12, v8, v9
	v_mul_f32_e32 v46, v31, v8
	v_pk_mul_f32 v[6:7], v[30:31], v[8:9] op_sel_hi:[0,1]
	v_mul_f32_e32 v47, v31, v9
	v_pk_mul_f32 v[8:9], v[30:31], v[2:3] op_sel_hi:[0,1]
	s_mov_b32 s20, 0x10000
	v_add3_u32 v32, 0, v135, v136
	v_pk_mul_f32 v[6:7], v[128:129], v[6:7] op_sel_hi:[0,1]
	v_cvt_pk_bf16_f32 v13, v2, v3
	v_mul_f32_e32 v4, v31, v2
	v_pk_mul_f32 v[8:9], v[128:129], v[8:9] op_sel_hi:[0,1]
	v_add_co_u32_e32 v2, vcc, s20, v26
	v_pk_mul_f32 v[22:23], v[128:129], v[22:23] op_sel_hi:[0,1]
	v_pk_mul_f32 v[14:15], v[128:129], v[14:15] op_sel_hi:[0,1]
	v_pk_mul_f32 v[16:17], v[128:129], v[16:17] op_sel_hi:[0,1]
	v_pk_mul_f32 v[18:19], v[128:129], v[18:19] op_sel_hi:[0,1]
	ds_write_b128 v39, v[10:13] offset:16
	ds_write_b128 v32, v[22:25] offset:1024
	ds_write_b128 v32, v[14:17] offset:1040
	ds_write_b128 v32, v[18:21] offset:1056
	ds_write_b128 v32, v[6:9] offset:1072
	v_mul_f32_e32 v10, v31, v3
	v_cvt_pk_bf16_f32 v6, v33, v34
	v_cvt_pk_bf16_f32 v7, v35, v36
	v_cvt_pk_bf16_f32 v8, v37, v38
	v_cvt_pk_bf16_f32 v9, v40, v41
	v_addc_co_u32_e32 v3, vcc, 0, v27, vcc
	global_store_dwordx4 v[2:3], v[6:9], off
	v_mov_b32_e32 v3, 0
	v_mov_b32_e32 v2, 0
	v_cvt_pk_bf16_f32 v6, v42, v43
	v_cvt_pk_bf16_f32 v7, v44, v45
	v_cvt_pk_bf16_f32 v8, v46, v47
	v_cvt_pk_bf16_f32 v9, v4, v10
	global_store_dwordx4 v[28:29], v[6:9], off offset:16
	v_mov_b32_e32 v4, 0
	v_mov_b32_e32 v11, 0
	v_mov_b32_e32 v7, 0
	v_mov_b32_e32 v6, 0
	v_mov_b32_e32 v9, 0
	v_mov_b32_e32 v8, 0
	v_mov_b32_e32 v10, 0
	v_mov_b32_e32 v13, 0
	v_mov_b32_e32 v12, 0
	v_mov_b32_e32 v15, 0
	v_mov_b32_e32 v14, 0
	v_mov_b32_e32 v17, 0
	v_mov_b32_e32 v16, 0
	s_and_saveexec_b64 s[20:21], s[4:5]
	s_cbranch_execz .LBB0_1034
	v_readfirstlane_b32 s98, v124
	s_nop 0
	s_cmpk_ge_i32 s98, 0x40
	s_cbranch_scc1 .Lfc2_entry
	v_or3_b32 v122, v134, v114, s72
	v_cmp_gt_i32_e32 vcc, 3, v124
	s_and_saveexec_b64 s[4:5], vcc
	s_xor_b64 s[4:5], exec, s[4:5]
	s_cbranch_execz .LBB0_1013
	v_mov_b32_e32 v5, 0
	v_mov_b32_e32 v4, 0
	v_mov_b32_e32 v3, 0
	v_mov_b32_e32 v2, 0
	v_mov_b32_e32 v13, 0
	v_mov_b32_e32 v12, 0
	v_mov_b32_e32 v11, 0
	v_mov_b32_e32 v10, 0
	v_mov_b32_e32 v9, 0
	v_mov_b32_e32 v8, 0
	v_mov_b32_e32 v7, 0
	v_mov_b32_e32 v6, 0
	v_mov_b32_e32 v17, 0
	v_mov_b32_e32 v16, 0
	v_mov_b32_e32 v15, 0
	v_mov_b32_e32 v14, 0
	s_and_saveexec_b64 s[22:23], s[6:7]
	s_cbranch_execz .LBB0_1012
	s_load_dwordx2 s[24:25], s[18:19], 0x40
	v_ashrrev_i32_e32 v125, 31, v124
	v_lshl_add_u64 v[2:3], v[120:121], 0, v[124:125]
	s_waitcnt lgkmcnt(0)
	v_mov_b64_e32 v[4:5], s[24:25]
	v_mad_u64_u32 v[4:5], s[24:25], v2, s69, v[4:5]
	v_mov_b32_e32 v2, v5
	v_mad_u64_u32 v[2:3], s[24:25], v3, s69, v[2:3]
	v_mov_b32_e32 v5, v2
	v_lshlrev_b32_e32 v2, 2, v122
	v_mov_b32_e32 v3, v0
	v_lshl_add_u64 v[2:3], v[4:5], 0, v[2:3]
	global_load_dwordx4 v[14:17], v[2:3], off
	global_load_dwordx4 v[6:9], v[2:3], off offset:16
	global_load_dwordx4 v[10:13], v[2:3], off offset:32
	s_nop 0
	global_load_dwordx4 v[2:5], v[2:3], off offset:48
